# in-proj GEMM: each wave's two LDS-DMA pieces cover both 64-B halves of the same 16 rows (same LDS image); no setprio
# baseline (speedup 1.0000x reference)
; #define PG8_STAGE(bufoff, gbase, voff) do { _Pragma("unroll") for (int _i = 0; _i < 2; ++_i) \
;         __builtin_amdgcn_global_load_lds((const unsigned*)((const char*)(gbase) + (voff)[_i]), (LAS unsigned*)(lds + (bufoff) + ldsw + _i * 8192), 16, 0, 0); } while (0)
; #define PG8_WAIT_V(n) asm volatile("s_waitcnt vmcnt(" #n ")" ::: "memory")
; #define PG8_BAR __builtin_amdgcn_s_barrier()
; template <class Epi>
; __device__ __forceinline__ void gemm_phase(LAS unsigned char* lds, const Gemm g, const StaticOrder& S, const Epi& E, const int tid) {
;     const int wid = __builtin_amdgcn_readfirstlane(tid >> 6), lane = tid & 63, wr = wid >> 2, wc = wid & 3, fr = lane & 15, fq = lane >> 4;
;     const int K = g.K, nt = K / BK;
;     unsigned voffA[2], voffB[2];
; #pragma unroll
;     for (int i = 0; i < 2; ++i) { int R, C; stage_rc(tid * 16 + i * 8192, R, C); const int Rb = Epi::BJ_ADJ ? ((R >> 5) * 64 + perm32(R & 31)) : (Epi::PERM ? ((R & ~31) + perm32(R & 31)) : R);
;         voffA[i] = (unsigned)(R * K + C) * 2u; voffB[i] = (unsigned)(Rb * K + C) * 2u; }
;     const size_t kstep = (size_t)(BK * 2);
;     const size_t hstep = (size_t)HALF * K * 2;
;     const size_t tstep = 2 * hstep;
;     const size_t hstepB = Epi::BJ_ADJ ? (size_t)32 * K * 2 : hstep;
;     const unsigned ldsw = (unsigned)wid * 1024u;
;     const int aoff = lds_byte(wr * 64 + fr, fq * 8), boff = lds_byte(wc * 32 + fr, fq * 8);
;     ...
;     const char* cA = (const char*)g.A + (size_t)cur.pm * tstep; const char* cB = (const char*)g.Bt + (size_t)cur.pn * tstep;
;     PG8_STAGE(PG8_SB(0, 0), cB, voffB); PG8_STAGE(PG8_SA(0, 0), cA, voffA); PG8_STAGE(PG8_SB(0, 1), cB + hstepB, voffB); PG8_STAGE(PG8_SA(0, 1), cA + hstep, voffA);
;     if (wr == 1) PG8_BAR;
;     PG8_WAIT_V(4); PG8_BAR;
;     PG8_STAGE(PG8_SB(1, 0), cB + kstep, voffB); PG8_STAGE(PG8_SA(1, 0), cA + kstep, voffA); PG8_STAGE(PG8_SB(1, 1), cB + hstepB + kstep, voffB);
;     PG8_WAIT_V(6); PG8_BAR;
.LBB0_324:
	s_andn2_b64 vcc, exec, s[0:1]
	s_cbranch_vccnz .LBB0_337
	v_readlane_b32 s0, v253, 15
	v_readlane_b32 s1, v253, 16
	s_andn2_b64 vcc, exec, s[0:1]
	v_readfirstlane_b32 s20, v72
	s_cbranch_vccnz .LBB0_337
	v_lshlrev_b32_e32 v1, 4, v72
	v_add_u32_e32 v0, 0x2000, v1
	v_ashrrev_i32_e32 v2, 31, v0
	v_lshrrev_b32_e32 v2, 22, v2
	v_add_u32_e32 v2, v0, v2
	v_ashrrev_i32_e32 v4, 10, v2
	v_mul_i32_i24_e32 v2, 0x400, v4
	v_sub_u32_e32 v0, v0, v2
	v_lshrrev_b32_e32 v2, 4, v0
	v_bitop3_b32 v0, v2, v0, 32 bitop3:0x6c
	v_ashrrev_i32_e32 v2, 31, v0
	v_lshrrev_b32_e32 v2, 26, v2
	v_add_u32_e32 v2, v0, v2
	v_lshlrev_b32_e32 v7, 3, v4
	v_ashrrev_i32_e32 v5, 6, v2
	v_and_b32_e32 v7, -16, v7
	v_add_u32_e32 v7, v5, v7
	v_lshrrev_b32_e32 v8, 2, v7
	v_lshlrev_b32_e32 v9, 1, v7
	v_and_b32_e32 v2, 0xc0, v2
	v_and_b32_e32 v6, 3, v5
	v_and_b32_e32 v8, 4, v8
	v_and_b32_e32 v9, 0xfffd8, v9
	v_sub_u32_e32 v0, v0, v2
	v_or3_b32 v8, v6, v8, v9
	v_lshlrev_b32_e32 v6, 5, v4
	v_ashrrev_i16_sdwa v0, v183, sext(v0) dst_sel:DWORD dst_unused:UNUSED_PAD src0_sel:DWORD src1_sel:BYTE_0
	v_and_b32_e32 v9, 32, v6
	v_bfe_i32 v6, v0, 0, 16
	v_add_lshl_u32 v2, v9, v6, 1
	v_lshl_add_u32 v0, v8, 12, v2
	v_lshl_add_u32 v132, v7, 12, v2
	v_bfe_i32 v2, v72, 27, 1
	v_lshrrev_b32_e32 v2, 22, v2
	v_add_u32_e32 v2, v1, v2
	v_and_b32_e32 v2, 0xfffffc00, v2
	v_sub_u32_e32 v1, v1, v2
	v_lshrrev_b32_e32 v2, 4, v1
	v_ashrrev_i32_e32 v8, 31, v72
	v_bitop3_b32 v1, v2, v1, 32 bitop3:0x6c
	v_lshrrev_b32_e32 v8, 26, v8
	v_ashrrev_i32_e32 v2, 31, v1
	v_add_u32_e32 v8, v72, v8
	v_lshrrev_b32_e32 v2, 26, v2
	v_ashrrev_i32_e32 v8, 6, v8
	v_add_u32_e32 v2, v1, v2
	v_lshlrev_b32_e32 v10, 3, v8
	v_ashrrev_i32_e32 v7, 6, v2
	v_and_b32_e32 v10, -16, v10
	s_mul_i32 s0, s22, 0x3c00000
	v_add_u32_e32 v10, v7, v10
	s_add_u32 s24, s66, s0
	v_lshrrev_b32_e32 v11, 2, v10
	v_lshlrev_b32_e32 v12, 1, v10
	v_and_b32_e32 v2, 0xc0, v2
	s_addc_u32 s25, s67, 0
	s_ashr_i32 s1, s20, 6
	v_and_b32_e32 v9, 3, v7
	v_and_b32_e32 v11, 4, v11
	v_and_b32_e32 v12, 0xfffd8, v12
	v_sub_u32_e32 v1, v1, v2
	s_ashr_i32 s0, s20, 8
	s_lshl_b32 s38, s1, 11
	s_lshr_b32 s98, s1, 1
	s_and_b32 s99, s1, 1
	v_or3_b32 v11, v9, v11, v12
	v_lshlrev_b32_e32 v9, 5, v8
	v_ashrrev_i16_sdwa v1, v183, sext(v1) dst_sel:DWORD dst_unused:UNUSED_PAD src0_sel:DWORD src1_sel:BYTE_0
	v_readlane_b32 s4, v253, 31
	v_and_b32_e32 v12, 32, v9
	v_bfe_i32 v9, v1, 0, 16
	v_readlane_b32 s5, v253, 32
	s_add_u32 s18, s24, s4
	v_add_lshl_u32 v1, v12, v9, 1
	s_addc_u32 s19, s25, s5
	s_add_i32 s39, s38, 0
	v_lshl_add_u32 v2, v11, 12, v1
	s_lshl_b32 s100, s98, 6
	s_lshl_b32 s101, s99, 2
	s_add_i32 s100, s100, s101
	s_lshr_b32 s101, s98, 1
	s_lshl_b32 s101, s101, 6
	s_sub_i32 s100, s100, s101
	s_and_b32 s101, s98, 1
	s_lshl_b32 s101, s101, 2
	s_sub_i32 s100, s100, s101
	s_lshl_b32 s100, s100, 12
	s_lshl_b32 s101, s99, 6
	s_sub_i32 s100, s100, s101
	s_add_i32 s101, s100, 0xfff80040
	v_add_u32_e32 v2, s100, v2
	v_add_u32_e32 v0, s101, v0
	s_sub_i32 s100, s1, s98
	s_lshl_b32 s100, s100, 16
	s_lshl_b32 s101, s99, 6
	s_sub_i32 s100, s100, s101
	s_add_i32 s101, s100, 0xfffc0040
	s_add_i32 m0, s39, 0x10000
	v_readlane_b32 s4, v253, 35
	global_load_lds_dwordx4 v2, s[18:19]
	s_add_i32 m0, s39, 0x10400
	v_lshl_add_u32 v134, v10, 12, v1
	v_add_u32_e32 v134, s100, v134
	v_add_u32_e32 v132, s101, v132
	global_load_lds_dwordx4 v0, s[18:19]
	s_mov_b32 m0, s39
	v_readlane_b32 s5, v253, 36
	s_add_i32 s40, s39, 0x400
	s_nop 3
	global_load_lds_dwordx4 v134, s[4:5]
	s_mov_b32 m0, s40
	s_nop 0
	global_load_lds_dwordx4 v132, s[4:5]
	s_add_u32 s4, s18, 0x20000
	s_addc_u32 s5, s19, 0
	s_add_i32 m0, s39, 0x14000
	s_add_i32 s41, s39, 0x4000
	global_load_lds_dwordx4 v2, s[4:5]
	s_add_i32 m0, s39, 0x14400
	s_add_i32 s42, s39, 0x4400
	global_load_lds_dwordx4 v0, s[4:5]
	v_readlane_b32 s4, v253, 37
	s_mov_b32 m0, s41
	v_readlane_b32 s5, v253, 38
	s_cmp_lg_u32 s0, 1
	s_nop 3
	global_load_lds_dwordx4 v134, s[4:5]
	s_mov_b32 m0, s42
	s_nop 0
	global_load_lds_dwordx4 v132, s[4:5]
	s_cbranch_scc1 .LBB0_328
	s_barrier
.LBB0_328:
	v_lshl_add_u64 v[10:11], s[18:19], 0, v[2:3]
	v_mov_b32_e32 v1, v3
	v_readlane_b32 s14, v253, 35
	v_lshl_add_u64 v[12:13], s[18:19], 0, v[0:1]
	v_mov_b32_e32 v135, v3
	v_readlane_b32 s15, v253, 36
	s_and_b32 s1, s1, 3
	s_add_i32 m0, s39, 0x18000
	v_lshl_add_u64 v[10:11], v[10:11], 0, s[30:31]
	v_lshl_add_u64 v[14:15], s[14:15], 0, v[134:135]
	v_mov_b32_e32 v133, v3
	s_lshl_b32 s6, s0, 13
	s_lshl_b32 s7, s1, 12
	s_waitcnt vmcnt(4)
	s_barrier
	global_load_lds_dwordx4 v[10:11], off
	v_lshl_add_u64 v[10:11], v[12:13], 0, s[30:31]
	s_add_i32 m0, s39, 0x18400
	s_add_i32 s43, s39, 0x8000
	s_add_i32 s46, s39, 0x8400
	v_lshl_add_u64 v[16:17], s[14:15], 0, v[132:133]
	global_load_lds_dwordx4 v[10:11], off
	v_lshl_add_u64 v[10:11], v[14:15], 0, s[30:31]
	s_mov_b32 m0, s43
	s_add_u32 s4, s18, 0x20080
	global_load_lds_dwordx4 v[10:11], off
	v_lshl_add_u64 v[10:11], v[16:17], 0, s[30:31]
	s_mov_b32 m0, s46
	s_addc_u32 s5, s19, 0
	global_load_lds_dwordx4 v[10:11], off
	s_add_i32 m0, s39, 0x1c000
	v_lshl_add_u64 v[10:11], s[4:5], 0, v[2:3]
	global_load_lds_dwordx4 v[10:11], off
	v_lshl_add_u64 v[10:11], s[4:5], 0, v[0:1]
	s_add_i32 m0, s39, 0x1c400
	v_lshlrev_b32_e32 v13, 2, v72
	global_load_lds_dwordx4 v[10:11], off
	v_lshrrev_b32_e32 v11, 1, v72
	v_and_b32_e32 v11, 24, v11
	v_and_b32_e32 v10, 15, v72
	v_lshlrev_b32_e32 v12, 1, v11
	v_lshl_or_b32 v12, v10, 6, v12
	v_and_b32_e32 v13, 32, v13
	v_bitop3_b32 v14, v12, s6, v13 bitop3:0xde
	v_bitop3_b32 v140, s7, v12, v13 bitop3:0xf6
	v_and_b32_e32 v12, 7, v72
	v_cmp_lt_u32_e64 s[4:5], 7, v10
	v_lshl_or_b32 v141, s0, 6, v12
	s_lshl_b32 s0, s1, 6
	v_cndmask_b32_e64 v10, 0, 32, s[4:5]
	v_or3_b32 v142, s0, v10, v11
	v_lshlrev_b32_e32 v10, 15, v8
	v_and_b32_e32 v10, 0xffff0000, v10
	v_lshl_add_u32 v7, v7, 12, v10
	v_and_b32_e32 v8, 1, v8
	v_lshl_or_b32 v7, v8, 6, v7
	v_lshl_add_u32 v136, v9, 1, v7
	v_add_u32_e32 v136, s100, v136
	v_lshlrev_b32_e32 v7, 15, v4
	v_and_b32_e32 v7, 0xffff0000, v7
	s_waitcnt vmcnt(6)
	v_lshl_add_u32 v5, v5, 12, v7
	v_and_b32_e32 v4, 1, v4
	v_lshl_or_b32 v4, v4, 6, v5
	v_readlane_b32 s0, v253, 33
	s_mov_b32 s47, 0
	v_mov_b32_e32 v137, v3
	v_lshl_add_u32 v138, v6, 1, v4
	v_add_u32_e32 v138, s101, v138
	v_mov_b32_e32 v139, v3
	v_add_u32_e32 v143, 0, v14
	v_readlane_b32 s48, v253, 30
	s_mov_b32 s49, s0
	s_barrier
	v_readlane_b32 s1, v253, 34

; #define PG8_STAGE(bufoff, gbase, voff) do { _Pragma("unroll") for (int _i = 0; _i < 2; ++_i) \
;         __builtin_amdgcn_global_load_lds((const unsigned*)((const char*)(gbase) + (voff)[_i]), (LAS unsigned*)(lds + (bufoff) + ldsw + _i * 8192), 16, 0, 0); } while (0)
; #define PG8_LDA(dst, b, h) do { _Pragma("unroll") for (int m = 0; m < 4; ++m) _Pragma("unroll") for (int k = 0; k < 2; ++k) dst[m][k] = *(const LAS h8*)(lds + PG8_SA(b, h) + aoff + m * 2048 + k * 1024); } while (0)
; #define PG8_LDB(dst, b, h) do { _Pragma("unroll") for (int n = 0; n < 2; ++n) _Pragma("unroll") for (int k = 0; k < 2; ++k) dst[n][k] = *(const LAS h8*)(lds + PG8_SB(b, h) + boff + n * 2048 + k * 1024); } while (0)
; #define PG8_WAIT_V(n) asm volatile("s_waitcnt vmcnt(" #n ")" ::: "memory")
; #define PG8_WAIT_L(n) asm volatile("s_waitcnt lgkmcnt(" #n ")" ::: "memory")
; #define PG8_BAR __builtin_amdgcn_s_barrier()
; #define PG8_SCHED __builtin_amdgcn_sched_barrier(0)
; template <class Epi>
; __device__ __forceinline__ void gemm_phase(LAS unsigned char* lds, const Gemm g, const StaticOrder& S, const Epi& E, const int tid) {
;     ...
;             PG8_LDB(B0, 0, 0); PG8_SCHED; PG8_LDA(At, 0, 0); PG8_STAGE(PG8_SA(1, 1), a1 + hstep, voffA);
;             PG8_WAIT_L(8); PG8_BAR; PG8_WAIT_L(0); PG8_MMA(0, 0, At, B0); PG8_BAR; PG8_SCHED;
;             PG8_LDB(B1, 0, 1); PG8_STAGE(PG8_SB(0, 0), b2, voffB);
;             PG8_BAR; PG8_WAIT_L(0); PG8_MMA(0, 1, At, B1); PG8_BAR;
;             PG8_LDA(At, 0, 1); PG8_STAGE(PG8_SA(0, 0), a2, voffA);
;             PG8_BAR; PG8_WAIT_L(0); PG8_MMA(1, 0, At, B0); PG8_BAR; PG8_SCHED;
;             PG8_STAGE(PG8_SB(0, 1), b2 + hstepB, voffB);
;             PG8_WAIT_V(6); PG8_BAR; PG8_MMA(1, 1, At, B1); PG8_BAR;
.LBB0_332:
	s_add_u32 s18, s14, 0xfff80080
	s_addc_u32 s19, s15, -1
	s_add_i32 s55, 0, 0x10000
	v_add_u32_e32 v157, s55, v140
	ds_read_b128 v[144:147], v157
	ds_read_b128 v[162:165], v157 offset:1024
	ds_read_b128 v[166:169], v157 offset:2048
	ds_read_b128 v[170:173], v157 offset:3072
	s_cmp_eq_u32 s54, 28
	s_cselect_b32 s23, s9, s19
	s_cselect_b32 s22, s50, s18
	s_cselect_b32 s19, s1, s53
	s_cselect_b32 s18, s51, s52
	v_lshl_add_u64 v[178:179], s[14:15], 0, v[136:137]
	s_add_i32 m0, s39, 0xc000
	ds_read_b128 v[174:177], v143
	ds_read_b128 v[190:193], v143 offset:1024
	ds_read_b128 v[194:197], v143 offset:2048
	ds_read_b128 v[198:201], v143 offset:3072
	ds_read_b128 v[202:205], v143 offset:4096
	ds_read_b128 v[206:209], v143 offset:5120
	ds_read_b128 v[210:213], v143 offset:6144
	ds_read_b128 v[214:217], v143 offset:7168
	global_load_lds_dwordx4 v[178:179], off
	v_lshl_add_u64 v[178:179], s[14:15], 0, v[138:139]
	s_add_i32 m0, s39, 0xc400
	s_nop 0
	global_load_lds_dwordx4 v[178:179], off
	s_waitcnt lgkmcnt(8)
	s_barrier
	s_waitcnt lgkmcnt(0)
	s_waitcnt lgkmcnt(0)
	v_mfma_f32_16x16x32_bf16 v[124:127], v[144:147], v[174:177], v[124:127]
	v_mfma_f32_16x16x32_bf16 v[128:131], v[166:169], v[174:177], v[128:131]
	v_mfma_f32_16x16x32_bf16 v[108:111], v[144:147], v[194:197], v[108:111]
	v_mfma_f32_16x16x32_bf16 v[112:115], v[166:169], v[194:197], v[112:115]
	v_mfma_f32_16x16x32_bf16 v[92:95], v[144:147], v[202:205], v[92:95]
	v_mfma_f32_16x16x32_bf16 v[96:99], v[166:169], v[202:205], v[96:99]
	v_mfma_f32_16x16x32_bf16 v[76:79], v[144:147], v[210:213], v[76:79]
	v_mfma_f32_16x16x32_bf16 v[80:83], v[166:169], v[210:213], v[80:83]
	v_mfma_f32_16x16x32_bf16 v[124:127], v[162:165], v[190:193], v[124:127]
	v_mfma_f32_16x16x32_bf16 v[128:131], v[170:173], v[190:193], v[128:131]
	v_mfma_f32_16x16x32_bf16 v[108:111], v[162:165], v[198:201], v[108:111]
	v_mfma_f32_16x16x32_bf16 v[112:115], v[170:173], v[198:201], v[112:115]
	v_mfma_f32_16x16x32_bf16 v[92:95], v[162:165], v[206:209], v[92:95]
	v_mfma_f32_16x16x32_bf16 v[96:99], v[170:173], v[206:209], v[96:99]
	v_mfma_f32_16x16x32_bf16 v[76:79], v[162:165], v[214:217], v[76:79]
	v_mfma_f32_16x16x32_bf16 v[80:83], v[170:173], v[214:217], v[80:83]
	s_barrier
	s_add_i32 s58, 0, 0x14000
	s_add_i32 s55, s55, s38
	v_add_u32_e32 v157, s58, v140
	v_lshl_add_u64 v[178:179], s[18:19], 0, v[2:3]
	s_mov_b32 m0, s55
	ds_read_b128 v[218:221], v157
	ds_read_b128 v[222:225], v157 offset:1024
	ds_read_b128 v[226:229], v157 offset:2048
	ds_read_b128 v[230:233], v157 offset:3072
	global_load_lds_dwordx4 v[178:179], off
	v_lshl_add_u64 v[234:235], s[18:19], 0, v[0:1]
	s_add_i32 m0, s55, 0x400
	s_nop 0
	global_load_lds_dwordx4 v[234:235], off
	s_barrier
	s_waitcnt lgkmcnt(0)
	s_waitcnt lgkmcnt(0)
	v_mfma_f32_16x16x32_bf16 v[116:119], v[218:221], v[174:177], v[116:119]
	v_mfma_f32_16x16x32_bf16 v[120:123], v[226:229], v[174:177], v[120:123]
	v_mfma_f32_16x16x32_bf16 v[100:103], v[218:221], v[194:197], v[100:103]
	v_mfma_f32_16x16x32_bf16 v[104:107], v[226:229], v[194:197], v[104:107]
	v_mfma_f32_16x16x32_bf16 v[84:87], v[218:221], v[202:205], v[84:87]
	v_mfma_f32_16x16x32_bf16 v[88:91], v[226:229], v[202:205], v[88:91]
	v_mfma_f32_16x16x32_bf16 v[68:71], v[218:221], v[210:213], v[68:71]
	v_mfma_f32_16x16x32_bf16 v[72:75], v[226:229], v[210:213], v[72:75]
	v_mfma_f32_16x16x32_bf16 v[116:119], v[222:225], v[190:193], v[116:119]
	v_mfma_f32_16x16x32_bf16 v[120:123], v[230:233], v[190:193], v[120:123]
	v_mfma_f32_16x16x32_bf16 v[100:103], v[222:225], v[198:201], v[100:103]
	v_mfma_f32_16x16x32_bf16 v[104:107], v[230:233], v[198:201], v[104:107]
	v_mfma_f32_16x16x32_bf16 v[84:87], v[222:225], v[206:209], v[84:87]
	v_mfma_f32_16x16x32_bf16 v[88:91], v[230:233], v[206:209], v[88:91]
	v_mfma_f32_16x16x32_bf16 v[68:71], v[222:225], v[214:217], v[68:71]
	v_mfma_f32_16x16x32_bf16 v[72:75], v[230:233], v[214:217], v[72:75]
	s_mov_b32 m0, s39
	v_lshl_add_u64 v[236:237], s[22:23], 0, v[134:135]
	s_barrier
	ds_read_b128 v[174:177], v143 offset:16384
	ds_read_b128 v[190:193], v143 offset:17408
	ds_read_b128 v[194:197], v143 offset:18432
	ds_read_b128 v[198:201], v143 offset:19456
	ds_read_b128 v[202:205], v143 offset:20480
	ds_read_b128 v[206:209], v143 offset:21504
	ds_read_b128 v[210:213], v143 offset:22528
	ds_read_b128 v[214:217], v143 offset:23552
	global_load_lds_dwordx4 v[236:237], off
	v_lshl_add_u64 v[238:239], s[22:23], 0, v[132:133]
	s_mov_b32 m0, s40
	s_nop 0
	global_load_lds_dwordx4 v[238:239], off
	s_barrier
	s_waitcnt lgkmcnt(0)
	s_waitcnt lgkmcnt(0)
	v_mfma_f32_16x16x32_bf16 v[60:63], v[144:147], v[174:177], v[60:63]
	v_mfma_f32_16x16x32_bf16 v[64:67], v[166:169], v[174:177], v[64:67]
	v_mfma_f32_16x16x32_bf16 v[44:47], v[144:147], v[194:197], v[44:47]
	v_mfma_f32_16x16x32_bf16 v[48:51], v[166:169], v[194:197], v[48:51]
	v_mfma_f32_16x16x32_bf16 v[28:31], v[144:147], v[202:205], v[28:31]
	v_mfma_f32_16x16x32_bf16 v[32:35], v[166:169], v[202:205], v[32:35]
	v_mfma_f32_16x16x32_bf16 v[12:15], v[144:147], v[210:213], v[12:15]
	v_mfma_f32_16x16x32_bf16 v[16:19], v[166:169], v[210:213], v[16:19]
	v_mfma_f32_16x16x32_bf16 v[60:63], v[162:165], v[190:193], v[60:63]
	v_mfma_f32_16x16x32_bf16 v[64:67], v[170:173], v[190:193], v[64:67]
	v_mfma_f32_16x16x32_bf16 v[44:47], v[162:165], v[198:201], v[44:47]
	v_mfma_f32_16x16x32_bf16 v[48:51], v[170:173], v[198:201], v[48:51]
	v_mfma_f32_16x16x32_bf16 v[28:31], v[162:165], v[206:209], v[28:31]
	v_mfma_f32_16x16x32_bf16 v[32:35], v[170:173], v[206:209], v[32:35]
	v_mfma_f32_16x16x32_bf16 v[12:15], v[162:165], v[214:217], v[12:15]
	v_mfma_f32_16x16x32_bf16 v[16:19], v[170:173], v[214:217], v[16:19]
	s_barrier
; #define PG8_STAGE(bufoff, gbase, voff) do { _Pragma("unroll") for (int _i = 0; _i < 2; ++_i) \
;         __builtin_amdgcn_global_load_lds((const unsigned*)((const char*)(gbase) + (voff)[_i]), (LAS unsigned*)(lds + (bufoff) + ldsw + _i * 8192), 16, 0, 0); } while (0)
; #define PG8_LDA(dst, b, h) do { _Pragma("unroll") for (int m = 0; m < 4; ++m) _Pragma("unroll") for (int k = 0; k < 2; ++k) dst[m][k] = *(const LAS h8*)(lds + PG8_SA(b, h) + aoff + m * 2048 + k * 1024); } while (0)
; #define PG8_LDB(dst, b, h) do { _Pragma("unroll") for (int n = 0; n < 2; ++n) _Pragma("unroll") for (int k = 0; k < 2; ++k) dst[n][k] = *(const LAS h8*)(lds + PG8_SB(b, h) + boff + n * 2048 + k * 1024); } while (0)
; #define PG8_WAIT_V(n) asm volatile("s_waitcnt vmcnt(" #n ")" ::: "memory")
; #define PG8_WAIT_L(n) asm volatile("s_waitcnt lgkmcnt(" #n ")" ::: "memory")
; #define PG8_BAR __builtin_amdgcn_s_barrier()
; #define PG8_SCHED __builtin_amdgcn_sched_barrier(0)
; template <class Epi>
; __device__ __forceinline__ void gemm_phase(LAS unsigned char* lds, const Gemm g, const StaticOrder& S, const Epi& E, const int tid) {
;     ...
;             PG8_BAR; PG8_WAIT_L(0); PG8_MMA(1, 0, At, B0); PG8_BAR; PG8_SCHED;
;             PG8_STAGE(PG8_SB(0, 1), b2 + hstepB, voffB);
;             PG8_WAIT_V(6); PG8_BAR; PG8_MMA(1, 1, At, B1); PG8_BAR;
;             PG8_LDB(B0, 1, 0); PG8_SCHED; PG8_LDA(At, 1, 0); PG8_STAGE(PG8_SA(0, 1), a2 + hstep, voffA);
;             PG8_WAIT_L(8); PG8_BAR; PG8_WAIT_L(0); PG8_MMA(0, 0, At, B0); PG8_BAR; PG8_SCHED;
;             PG8_LDB(B1, 1, 1); PG8_STAGE(PG8_SB(1, 0), b3, voffB);
;             PG8_BAR; PG8_WAIT_L(0); PG8_MMA(0, 1, At, B1); PG8_BAR;
;             PG8_LDA(At, 1, 1); PG8_STAGE(PG8_SA(1, 0), a3, voffA);
	s_add_u32 s56, s18, 0x20000
	s_addc_u32 s57, s19, 0
	s_add_i32 s55, s58, s38
	v_lshl_add_u64 v[144:145], s[56:57], 0, v[2:3]
	s_mov_b32 m0, s55
	s_nop 0
	global_load_lds_dwordx4 v[144:145], off
	v_lshl_add_u64 v[144:145], s[56:57], 0, v[0:1]
	s_add_i32 m0, s55, 0x400
	s_nop 0
	global_load_lds_dwordx4 v[144:145], off
	s_waitcnt vmcnt(6)
	s_barrier
	v_mfma_f32_16x16x32_bf16 v[52:55], v[218:221], v[174:177], v[52:55]
	v_mfma_f32_16x16x32_bf16 v[56:59], v[226:229], v[174:177], v[56:59]
	v_mfma_f32_16x16x32_bf16 v[36:39], v[218:221], v[194:197], v[36:39]
	v_mfma_f32_16x16x32_bf16 v[40:43], v[226:229], v[194:197], v[40:43]
	v_mfma_f32_16x16x32_bf16 v[20:23], v[218:221], v[202:205], v[20:23]
	v_mfma_f32_16x16x32_bf16 v[24:27], v[226:229], v[202:205], v[24:27]
	v_mfma_f32_16x16x32_bf16 v[8:11], v[218:221], v[210:213], v[8:11]
	v_mfma_f32_16x16x32_bf16 v[4:7], v[226:229], v[210:213], v[4:7]
	v_mfma_f32_16x16x32_bf16 v[52:55], v[222:225], v[190:193], v[52:55]
	v_mfma_f32_16x16x32_bf16 v[56:59], v[230:233], v[190:193], v[56:59]
	v_mfma_f32_16x16x32_bf16 v[36:39], v[222:225], v[198:201], v[36:39]
	v_mfma_f32_16x16x32_bf16 v[40:43], v[230:233], v[198:201], v[40:43]
	v_mfma_f32_16x16x32_bf16 v[20:23], v[222:225], v[206:209], v[20:23]
	v_mfma_f32_16x16x32_bf16 v[24:27], v[230:233], v[206:209], v[24:27]
	v_mfma_f32_16x16x32_bf16 v[8:11], v[222:225], v[214:217], v[8:11]
	v_mfma_f32_16x16x32_bf16 v[4:7], v[230:233], v[214:217], v[4:7]
	s_add_i32 s55, 0, 0x18000
	v_add_u32_e32 v157, s55, v140
	s_barrier
	ds_read_b128 v[144:147], v157
	ds_read_b128 v[162:165], v157 offset:1024
	ds_read_b128 v[166:169], v157 offset:2048
	ds_read_b128 v[170:173], v157 offset:3072
	s_add_u32 s22, s22, 0x80000
	s_addc_u32 s23, s23, 0
	s_mov_b32 m0, s41
	v_lshl_add_u64 v[218:219], s[22:23], 0, v[134:135]
	ds_read_b128 v[174:177], v143 offset:32768
	ds_read_b128 v[190:193], v143 offset:33792
	ds_read_b128 v[194:197], v143 offset:34816
	ds_read_b128 v[198:201], v143 offset:35840
	ds_read_b128 v[202:205], v143 offset:36864
	ds_read_b128 v[206:209], v143 offset:37888
	ds_read_b128 v[210:213], v143 offset:38912
	ds_read_b128 v[214:217], v143 offset:39936
	global_load_lds_dwordx4 v[218:219], off
	v_lshl_add_u64 v[218:219], s[22:23], 0, v[132:133]
	s_mov_b32 m0, s42
	s_nop 0
	global_load_lds_dwordx4 v[218:219], off
	s_waitcnt lgkmcnt(8)
	s_barrier
	s_waitcnt lgkmcnt(0)
	s_waitcnt lgkmcnt(0)
	v_mfma_f32_16x16x32_bf16 v[124:127], v[144:147], v[174:177], v[124:127]
	v_mfma_f32_16x16x32_bf16 v[128:131], v[166:169], v[174:177], v[128:131]
	v_mfma_f32_16x16x32_bf16 v[108:111], v[144:147], v[194:197], v[108:111]
	v_mfma_f32_16x16x32_bf16 v[112:115], v[166:169], v[194:197], v[112:115]
	v_mfma_f32_16x16x32_bf16 v[92:95], v[144:147], v[202:205], v[92:95]
	v_mfma_f32_16x16x32_bf16 v[96:99], v[166:169], v[202:205], v[96:99]
	v_mfma_f32_16x16x32_bf16 v[76:79], v[144:147], v[210:213], v[76:79]
	v_mfma_f32_16x16x32_bf16 v[80:83], v[166:169], v[210:213], v[80:83]
	v_mfma_f32_16x16x32_bf16 v[124:127], v[162:165], v[190:193], v[124:127]
	v_mfma_f32_16x16x32_bf16 v[128:131], v[170:173], v[190:193], v[128:131]
	v_mfma_f32_16x16x32_bf16 v[108:111], v[162:165], v[198:201], v[108:111]
	v_mfma_f32_16x16x32_bf16 v[112:115], v[170:173], v[198:201], v[112:115]
	v_mfma_f32_16x16x32_bf16 v[92:95], v[162:165], v[206:209], v[92:95]
	v_mfma_f32_16x16x32_bf16 v[96:99], v[170:173], v[206:209], v[96:99]
	v_mfma_f32_16x16x32_bf16 v[76:79], v[162:165], v[214:217], v[76:79]
	v_mfma_f32_16x16x32_bf16 v[80:83], v[170:173], v[214:217], v[80:83]
	s_barrier
	s_add_i32 s22, 0, 0x1c000
	s_add_i32 s23, s55, s38
	v_add_u32_e32 v157, s22, v140
	v_lshl_add_u64 v[178:179], v[178:179], 0, s[30:31]
	s_mov_b32 m0, s23
	ds_read_b128 v[218:221], v157
	ds_read_b128 v[222:225], v157 offset:1024
	ds_read_b128 v[226:229], v157 offset:2048
	ds_read_b128 v[230:233], v157 offset:3072
	global_load_lds_dwordx4 v[178:179], off
	v_lshl_add_u64 v[178:179], v[234:235], 0, s[30:31]
	s_add_i32 m0, s23, 0x400
	s_nop 0
	global_load_lds_dwordx4 v[178:179], off
	s_barrier
	s_waitcnt lgkmcnt(0)
	s_waitcnt lgkmcnt(0)
	v_mfma_f32_16x16x32_bf16 v[116:119], v[218:221], v[174:177], v[116:119]
	v_mfma_f32_16x16x32_bf16 v[120:123], v[226:229], v[174:177], v[120:123]
	v_mfma_f32_16x16x32_bf16 v[100:103], v[218:221], v[194:197], v[100:103]
	v_mfma_f32_16x16x32_bf16 v[104:107], v[226:229], v[194:197], v[104:107]
	v_mfma_f32_16x16x32_bf16 v[84:87], v[218:221], v[202:205], v[84:87]
	v_mfma_f32_16x16x32_bf16 v[88:91], v[226:229], v[202:205], v[88:91]
	v_mfma_f32_16x16x32_bf16 v[68:71], v[218:221], v[210:213], v[68:71]
	v_mfma_f32_16x16x32_bf16 v[72:75], v[226:229], v[210:213], v[72:75]
	v_mfma_f32_16x16x32_bf16 v[116:119], v[222:225], v[190:193], v[116:119]
	v_mfma_f32_16x16x32_bf16 v[120:123], v[230:233], v[190:193], v[120:123]
	v_mfma_f32_16x16x32_bf16 v[100:103], v[222:225], v[198:201], v[100:103]
	v_mfma_f32_16x16x32_bf16 v[104:107], v[230:233], v[198:201], v[104:107]
	v_mfma_f32_16x16x32_bf16 v[84:87], v[222:225], v[206:209], v[84:87]
	v_mfma_f32_16x16x32_bf16 v[88:91], v[230:233], v[206:209], v[88:91]
	v_mfma_f32_16x16x32_bf16 v[68:71], v[222:225], v[214:217], v[68:71]
	v_mfma_f32_16x16x32_bf16 v[72:75], v[230:233], v[214:217], v[72:75]
	s_mov_b32 m0, s43
	v_lshl_add_u64 v[178:179], v[236:237], 0, s[30:31]
	s_barrier
	ds_read_b128 v[174:177], v143 offset:49152
	ds_read_b128 v[190:193], v143 offset:50176
	ds_read_b128 v[194:197], v143 offset:51200
	ds_read_b128 v[198:201], v143 offset:52224
	ds_read_b128 v[202:205], v143 offset:53248
	ds_read_b128 v[206:209], v143 offset:54272
	ds_read_b128 v[210:213], v143 offset:55296
	ds_read_b128 v[214:217], v143 offset:56320
	global_load_lds_dwordx4 v[178:179], off
	v_lshl_add_u64 v[178:179], v[238:239], 0, s[30:31]
	s_mov_b32 m0, s46
	s_nop 0
	global_load_lds_dwordx4 v[178:179], off
	s_barrier
; #define PG8_STAGE(bufoff, gbase, voff) do { _Pragma("unroll") for (int _i = 0; _i < 2; ++_i) \
;         __builtin_amdgcn_global_load_lds((const unsigned*)((const char*)(gbase) + (voff)[_i]), (LAS unsigned*)(lds + (bufoff) + ldsw + _i * 8192), 16, 0, 0); } while (0)
; #define PG8_WAIT_V(n) asm volatile("s_waitcnt vmcnt(" #n ")" ::: "memory")
; #define PG8_WAIT_L(n) asm volatile("s_waitcnt lgkmcnt(" #n ")" ::: "memory")
; #define PG8_BAR __builtin_amdgcn_s_barrier()
; #define PG8_SCHED __builtin_amdgcn_sched_barrier(0)
; template <class Epi>
; __device__ __forceinline__ void gemm_phase(LAS unsigned char* lds, const Gemm g, const StaticOrder& S, const Epi& E, const int tid) {
;     ...
;             PG8_BAR; PG8_WAIT_L(0); PG8_MMA(1, 0, At, B0); PG8_BAR; PG8_SCHED;
;             PG8_STAGE(PG8_SB(1, 1), b3 + hstepB, voffB);
;             PG8_WAIT_V(6); PG8_BAR; PG8_MMA(1, 1, At, B1); PG8_BAR;
;         }
;     __device__ __forceinline__ void operator()(f32x4 (&acc)[2][2][4][2], const pg8::Unit& u, int wr, int wc, int fr, int fq) const {
;         const bool hi = fr >= 8;
;         const int row0 = u.pm * 256 + wr * 64 + (fr & 7), col = u.pn * 256 + wc * 64 + fq * 8 + (hi ? 32 : 0);
; #pragma unroll
;         for (int ai = 0; ai < 2; ++ai)
; #pragma unroll
;             for (int m = 0; m < 4; ++m) {
;                 const h8 x0 = pack8(acc[ai][0][m][0], acc[ai][0][m][1]), x1 = pack8(acc[ai][1][m][0], acc[ai][1][m][1]);
;                 const i32x4 snd = hi ? __builtin_bit_cast(i32x4, x0) : __builtin_bit_cast(i32x4, x1);
;                 i32x4 rcv;
; #pragma unroll
;                 for (int d = 0; d < 4; ++d) rcv[d] = __builtin_amdgcn_update_dpp(0, snd[d], 0x128  , 0xF, 0xF, false);
;                 const h8 rv = __builtin_bit_cast(h8, rcv);
;                 const h8 vA = hi ? rv : x0;
;                 const h8 vB = hi ? x1 : rv;
;                 half_t* rowp = O + (size_t)(row0 + ai * 128 + m * 16) * NIN + col;
;                 __builtin_nontemporal_store(vA, (h8*)rowp); __builtin_nontemporal_store(vB, (h8*)(rowp + (size_t)8 * NIN)); }
	s_waitcnt lgkmcnt(0)
	s_waitcnt lgkmcnt(0)
	v_mfma_f32_16x16x32_bf16 v[60:63], v[144:147], v[174:177], v[60:63]
	v_mfma_f32_16x16x32_bf16 v[64:67], v[166:169], v[174:177], v[64:67]
	v_mfma_f32_16x16x32_bf16 v[44:47], v[144:147], v[194:197], v[44:47]
	v_mfma_f32_16x16x32_bf16 v[48:51], v[166:169], v[194:197], v[48:51]
	v_mfma_f32_16x16x32_bf16 v[28:31], v[144:147], v[202:205], v[28:31]
	v_mfma_f32_16x16x32_bf16 v[32:35], v[166:169], v[202:205], v[32:35]
	v_mfma_f32_16x16x32_bf16 v[12:15], v[144:147], v[210:213], v[12:15]
	v_mfma_f32_16x16x32_bf16 v[16:19], v[166:169], v[210:213], v[16:19]
	v_mfma_f32_16x16x32_bf16 v[60:63], v[162:165], v[190:193], v[60:63]
	v_mfma_f32_16x16x32_bf16 v[64:67], v[170:173], v[190:193], v[64:67]
	v_mfma_f32_16x16x32_bf16 v[44:47], v[162:165], v[198:201], v[44:47]
	v_mfma_f32_16x16x32_bf16 v[48:51], v[170:173], v[198:201], v[48:51]
	v_mfma_f32_16x16x32_bf16 v[28:31], v[162:165], v[206:209], v[28:31]
	v_mfma_f32_16x16x32_bf16 v[32:35], v[170:173], v[206:209], v[32:35]
	v_mfma_f32_16x16x32_bf16 v[12:15], v[162:165], v[214:217], v[12:15]
	v_mfma_f32_16x16x32_bf16 v[16:19], v[170:173], v[214:217], v[16:19]
	s_barrier
	s_add_u32 s18, s18, 0x20080
	s_addc_u32 s19, s19, 0
	s_add_i32 s22, s22, s38
	v_lshl_add_u64 v[144:145], s[18:19], 0, v[2:3]
	s_mov_b32 m0, s22
	s_nop 0
	global_load_lds_dwordx4 v[144:145], off
	v_lshl_add_u64 v[144:145], s[18:19], 0, v[0:1]
	s_add_i32 m0, s22, 0x400
	s_nop 0
	global_load_lds_dwordx4 v[144:145], off
	s_waitcnt vmcnt(6)
	s_barrier
	v_mfma_f32_16x16x32_bf16 v[52:55], v[218:221], v[174:177], v[52:55]
	v_mfma_f32_16x16x32_bf16 v[56:59], v[226:229], v[174:177], v[56:59]
	v_mfma_f32_16x16x32_bf16 v[36:39], v[218:221], v[194:197], v[36:39]
	v_mfma_f32_16x16x32_bf16 v[40:43], v[226:229], v[194:197], v[40:43]
	v_mfma_f32_16x16x32_bf16 v[20:23], v[218:221], v[202:205], v[20:23]
	v_mfma_f32_16x16x32_bf16 v[24:27], v[226:229], v[202:205], v[24:27]
	v_mfma_f32_16x16x32_bf16 v[8:11], v[218:221], v[210:213], v[8:11]
	v_mfma_f32_16x16x32_bf16 v[4:7], v[226:229], v[210:213], v[4:7]
	v_mfma_f32_16x16x32_bf16 v[52:55], v[222:225], v[190:193], v[52:55]
	v_mfma_f32_16x16x32_bf16 v[56:59], v[230:233], v[190:193], v[56:59]
	v_mfma_f32_16x16x32_bf16 v[36:39], v[222:225], v[198:201], v[36:39]
	v_mfma_f32_16x16x32_bf16 v[40:43], v[230:233], v[198:201], v[40:43]
	v_mfma_f32_16x16x32_bf16 v[20:23], v[222:225], v[206:209], v[20:23]
	v_mfma_f32_16x16x32_bf16 v[24:27], v[230:233], v[206:209], v[24:27]
	v_mfma_f32_16x16x32_bf16 v[8:11], v[222:225], v[214:217], v[8:11]
	v_mfma_f32_16x16x32_bf16 v[4:7], v[230:233], v[214:217], v[4:7]
	s_add_i32 s54, s54, 2
	s_add_u32 s14, s14, 0x100
	s_addc_u32 s15, s15, 0
	s_add_u32 s52, s52, 0x100
	s_addc_u32 s53, s53, 0
	s_cmp_gt_u32 s54, 29
	s_barrier
	s_cbranch_scc0 .LBB0_332
	v_cvt_pk_f16_f32 v124, v124, v125
	v_cvt_pk_f16_f32 v116, v116, v117
	v_cvt_pk_f16_f32 v130, v130, v131
	v_cvt_pk_f16_f32 v131, v122, v123
	v_cvt_pk_f16_f32 v128, v128, v129
	v_cvt_pk_f16_f32 v129, v120, v121
	v_cvt_pk_f16_f32 v121, v126, v127
	v_cvt_pk_f16_f32 v118, v118, v119
	v_cndmask_b32_e64 v117, v116, v124, s[4:5]
	v_mov_b32_e32 v147, v3
	v_cndmask_b32_e64 v122, v131, v130, s[4:5]
	v_cndmask_b32_e64 v119, v118, v121, s[4:5]
	v_mov_b32_dpp v147, v117 row_ror:8 row_mask:0xf bank_mask:0xf
	v_mov_b32_e32 v117, v3
	v_mov_b32_e32 v125, v3
	v_lshl_or_b32 v144, s48, 8, v142
	v_cndmask_b32_e64 v120, v129, v128, s[4:5]
	v_mov_b32_dpp v117, v119 row_ror:8 row_mask:0xf bank_mask:0xf
	v_mov_b32_e32 v119, v3
	v_mov_b32_dpp v125, v122 row_ror:8 row_mask:0xf bank_mask:0xf
	v_lshl_add_u32 v146, s49, 8, v141
	v_ashrrev_i32_e32 v145, 31, v144
	v_mov_b32_dpp v119, v120 row_ror:8 row_mask:0xf bank_mask:0xf
	v_cndmask_b32_e64 v123, v130, v125, s[4:5]
	v_cndmask_b32_e64 v121, v121, v117, s[4:5]
	v_cndmask_b32_e64 v120, v124, v147, s[4:5]
	v_cndmask_b32_e64 v127, v125, v131, s[4:5]
	v_cndmask_b32_e64 v125, v117, v118, s[4:5]
	v_cndmask_b32_e64 v124, v147, v116, s[4:5]
	v_mov_b64_e32 v[116:117], s[36:37]
	v_cndmask_b32_e64 v122, v128, v119, s[4:5]
	v_cndmask_b32_e64 v126, v119, v129, s[4:5]
	v_mad_i64_i32 v[128:129], s[14:15], v146, s35, v[116:117]
	v_lshlrev_b64 v[118:119], 1, v[144:145]
	v_lshl_add_u64 v[128:129], v[128:129], 0, v[118:119]
	s_mov_b32 s1, 0x3c000
	global_store_dwordx4 v[128:129], v[120:123], off nt
	v_cvt_pk_f16_f32 v112, v112, v113
	v_cvt_pk_f16_f32 v104, v104, v105
	v_add_co_u32_e32 v120, vcc, s1, v128
	v_cvt_pk_f16_f32 v108, v108, v109
	s_nop 0
	v_addc_co_u32_e32 v121, vcc, 0, v129, vcc
	v_cvt_pk_f16_f32 v109, v100, v101
	global_store_dwordx4 v[120:121], v[124:127], off nt
	v_cvt_pk_f16_f32 v114, v114, v115
	v_cvt_pk_f16_f32 v106, v106, v107
	v_cndmask_b32_e64 v105, v104, v112, s[4:5]
	v_cndmask_b32_e64 v100, v109, v108, s[4:5]
	v_mov_b32_e32 v113, v3
	v_mov_b32_e32 v120, v3
	v_cndmask_b32_e64 v107, v106, v114, s[4:5]
	v_cvt_pk_f16_f32 v110, v110, v111
	v_cvt_pk_f16_f32 v111, v102, v103
	v_mov_b32_dpp v113, v100 row_ror:8 row_mask:0xf bank_mask:0xf
	v_mov_b32_dpp v120, v105 row_ror:8 row_mask:0xf bank_mask:0xf
	v_mov_b32_e32 v105, v3
	v_cndmask_b32_e64 v102, v111, v110, s[4:5]
	v_mov_b32_e32 v115, v3
	v_mov_b32_dpp v105, v107 row_ror:8 row_mask:0xf bank_mask:0xf
	v_cndmask_b32_e64 v100, v108, v113, s[4:5]
	v_or_b32_e32 v108, 16, v146
	v_mov_b32_dpp v115, v102 row_ror:8 row_mask:0xf bank_mask:0xf
	v_cndmask_b32_e64 v107, v105, v106, s[4:5]
	v_cndmask_b32_e64 v106, v120, v104, s[4:5]
	v_cndmask_b32_e64 v104, v113, v109, s[4:5]
	v_mad_i64_i32 v[108:109], s[14:15], v108, s35, v[116:117]
	v_cndmask_b32_e64 v103, v114, v105, s[4:5]
	v_cndmask_b32_e64 v102, v112, v120, s[4:5]
	v_cndmask_b32_e64 v101, v110, v115, s[4:5]
;     __device__ __forceinline__ void operator()(f32x4 (&acc)[2][2][4][2], const pg8::Unit& u, int wr, int wc, int fr, int fq) const {
;         const bool hi = fr >= 8;
;         const int row0 = u.pm * 256 + wr * 64 + (fr & 7), col = u.pn * 256 + wc * 64 + fq * 8 + (hi ? 32 : 0);
; #pragma unroll
;         for (int ai = 0; ai < 2; ++ai)
; #pragma unroll
;             for (int m = 0; m < 4; ++m) {
;                 const h8 x0 = pack8(acc[ai][0][m][0], acc[ai][0][m][1]), x1 = pack8(acc[ai][1][m][0], acc[ai][1][m][1]);
;                 const i32x4 snd = hi ? __builtin_bit_cast(i32x4, x0) : __builtin_bit_cast(i32x4, x1);
;                 i32x4 rcv;
; #pragma unroll
;                 for (int d = 0; d < 4; ++d) rcv[d] = __builtin_amdgcn_update_dpp(0, snd[d], 0x128  , 0xF, 0xF, false);
;                 const h8 rv = __builtin_bit_cast(h8, rcv);
;                 const h8 vA = hi ? rv : x0;
;                 const h8 vB = hi ? x1 : rv;
;                 half_t* rowp = O + (size_t)(row0 + ai * 128 + m * 16) * NIN + col;
;                 __builtin_nontemporal_store(vA, (h8*)rowp); __builtin_nontemporal_store(vB, (h8*)(rowp + (size_t)8 * NIN)); }
	v_lshl_add_u64 v[108:109], v[108:109], 0, v[118:119]
	global_store_dwordx4 v[108:109], v[100:103], off nt
	v_cndmask_b32_e64 v105, v115, v111, s[4:5]
	v_cvt_pk_f16_f32 v96, v96, v97
	v_add_co_u32_e32 v100, vcc, s1, v108
	v_cvt_pk_f16_f32 v88, v88, v89
	s_nop 0
	v_addc_co_u32_e32 v101, vcc, 0, v109, vcc
	v_cvt_pk_f16_f32 v92, v92, v93
	v_cvt_pk_f16_f32 v93, v84, v85
	global_store_dwordx4 v[100:101], v[104:107], off nt
	v_cvt_pk_f16_f32 v98, v98, v99
	v_cvt_pk_f16_f32 v90, v90, v91
	v_cndmask_b32_e64 v89, v88, v96, s[4:5]
	v_cndmask_b32_e64 v84, v93, v92, s[4:5]
	v_mov_b32_e32 v97, v3
	v_mov_b32_e32 v100, v3
	v_cndmask_b32_e64 v91, v90, v98, s[4:5]
	v_cvt_pk_f16_f32 v94, v94, v95
	v_cvt_pk_f16_f32 v95, v86, v87
	v_mov_b32_dpp v97, v84 row_ror:8 row_mask:0xf bank_mask:0xf
	v_mov_b32_dpp v100, v89 row_ror:8 row_mask:0xf bank_mask:0xf
	v_mov_b32_e32 v89, v3
	v_cndmask_b32_e64 v86, v95, v94, s[4:5]
	v_mov_b32_e32 v99, v3
	v_mov_b32_dpp v89, v91 row_ror:8 row_mask:0xf bank_mask:0xf
	v_cndmask_b32_e64 v84, v92, v97, s[4:5]
	v_or_b32_e32 v92, 32, v146
	v_mov_b32_dpp v99, v86 row_ror:8 row_mask:0xf bank_mask:0xf
	v_cndmask_b32_e64 v91, v89, v90, s[4:5]
	v_cndmask_b32_e64 v90, v100, v88, s[4:5]
	v_cndmask_b32_e64 v88, v97, v93, s[4:5]
	v_mad_i64_i32 v[92:93], s[14:15], v92, s35, v[116:117]
	v_cndmask_b32_e64 v87, v98, v89, s[4:5]
	v_cndmask_b32_e64 v86, v96, v100, s[4:5]
	v_cndmask_b32_e64 v85, v94, v99, s[4:5]
	v_lshl_add_u64 v[92:93], v[92:93], 0, v[118:119]
	global_store_dwordx4 v[92:93], v[84:87], off nt
	v_cndmask_b32_e64 v89, v99, v95, s[4:5]
	v_cvt_pk_f16_f32 v80, v80, v81
	v_add_co_u32_e32 v84, vcc, s1, v92
	v_cvt_pk_f16_f32 v72, v72, v73
	s_nop 0
	v_addc_co_u32_e32 v85, vcc, 0, v93, vcc
	v_cvt_pk_f16_f32 v76, v76, v77
	v_cvt_pk_f16_f32 v77, v68, v69
	global_store_dwordx4 v[84:85], v[88:91], off nt
	v_cvt_pk_f16_f32 v82, v82, v83
	v_cvt_pk_f16_f32 v74, v74, v75
	v_cndmask_b32_e64 v73, v72, v80, s[4:5]
	v_cndmask_b32_e64 v68, v77, v76, s[4:5]
	v_mov_b32_e32 v81, v3
	v_mov_b32_e32 v84, v3
	v_cndmask_b32_e64 v75, v74, v82, s[4:5]
	v_cvt_pk_f16_f32 v78, v78, v79
	v_cvt_pk_f16_f32 v79, v70, v71
	v_mov_b32_dpp v81, v68 row_ror:8 row_mask:0xf bank_mask:0xf
	v_mov_b32_dpp v84, v73 row_ror:8 row_mask:0xf bank_mask:0xf
	v_mov_b32_e32 v73, v3
	v_cndmask_b32_e64 v70, v79, v78, s[4:5]
	v_mov_b32_e32 v83, v3
	v_mov_b32_dpp v73, v75 row_ror:8 row_mask:0xf bank_mask:0xf
	v_cndmask_b32_e64 v68, v76, v81, s[4:5]
	v_or_b32_e32 v76, 48, v146
	v_mov_b32_dpp v83, v70 row_ror:8 row_mask:0xf bank_mask:0xf
	v_cndmask_b32_e64 v75, v73, v74, s[4:5]
	v_cndmask_b32_e64 v74, v84, v72, s[4:5]
	v_cndmask_b32_e64 v72, v81, v77, s[4:5]
	v_mad_i64_i32 v[76:77], s[14:15], v76, s35, v[116:117]
	v_cndmask_b32_e64 v71, v82, v73, s[4:5]
	v_cndmask_b32_e64 v70, v80, v84, s[4:5]
	v_cndmask_b32_e64 v69, v78, v83, s[4:5]
	v_lshl_add_u64 v[76:77], v[76:77], 0, v[118:119]
	global_store_dwordx4 v[76:77], v[68:71], off nt
	v_cndmask_b32_e64 v73, v83, v79, s[4:5]
	v_cvt_pk_f16_f32 v64, v64, v65
	v_add_co_u32_e32 v68, vcc, s1, v76
	v_cvt_pk_f16_f32 v56, v56, v57
	s_nop 0
	v_addc_co_u32_e32 v69, vcc, 0, v77, vcc
	global_store_dwordx4 v[68:69], v[72:75], off nt
	v_cvt_pk_f16_f32 v66, v66, v67
	v_cvt_pk_f16_f32 v58, v58, v59
	v_cndmask_b32_e64 v57, v56, v64, s[4:5]
	v_cvt_pk_f16_f32 v60, v60, v61
	v_cvt_pk_f16_f32 v61, v52, v53
	v_mov_b32_e32 v69, v3
	v_cndmask_b32_e64 v59, v58, v66, s[4:5]
	v_cvt_pk_f16_f32 v62, v62, v63
	v_cvt_pk_f16_f32 v63, v54, v55
	v_cndmask_b32_e64 v52, v61, v60, s[4:5]
	v_mov_b32_e32 v65, v3
	v_mov_b32_dpp v69, v57 row_ror:8 row_mask:0xf bank_mask:0xf
	v_mov_b32_e32 v57, v3
	v_add_u32_e32 v68, 0x80, v146
	v_cndmask_b32_e64 v54, v63, v62, s[4:5]
	v_mov_b32_dpp v65, v52 row_ror:8 row_mask:0xf bank_mask:0xf
	v_mov_b32_e32 v67, v3
	v_mov_b32_dpp v57, v59 row_ror:8 row_mask:0xf bank_mask:0xf
	v_cndmask_b32_e64 v52, v60, v65, s[4:5]
	v_mov_b32_dpp v67, v54 row_ror:8 row_mask:0xf bank_mask:0xf
	v_cndmask_b32_e64 v59, v57, v58, s[4:5]
	v_cndmask_b32_e64 v58, v69, v56, s[4:5]
	v_cndmask_b32_e64 v56, v65, v61, s[4:5]
	v_mad_i64_i32 v[60:61], s[14:15], v68, s35, v[116:117]
	v_cndmask_b32_e64 v55, v66, v57, s[4:5]
	v_cndmask_b32_e64 v54, v64, v69, s[4:5]
	v_cndmask_b32_e64 v53, v62, v67, s[4:5]
	v_lshl_add_u64 v[60:61], v[60:61], 0, v[118:119]
	global_store_dwordx4 v[60:61], v[52:55], off nt
	v_cndmask_b32_e64 v57, v67, v63, s[4:5]
	v_cvt_pk_f16_f32 v48, v48, v49
	v_add_co_u32_e32 v52, vcc, s1, v60
	v_cvt_pk_f16_f32 v40, v40, v41
	s_nop 0
	v_addc_co_u32_e32 v53, vcc, 0, v61, vcc
	v_cvt_pk_f16_f32 v44, v44, v45
; #define PG8_WAIT_V(n) asm volatile("s_waitcnt vmcnt(" #n ")" ::: "memory")
; #define PG8_BAR __builtin_amdgcn_s_barrier()
; template <class Epi>
; __device__ __forceinline__ void gemm_phase(LAS unsigned char* lds, const Gemm g, const StaticOrder& S, const Epi& E, const int tid) {
;     ...
;         E(acc, cur, wr, wc, fr, fq);
;         if (!has_next) break;
; #pragma unroll
;         for (int a = 0; a < 2; ++a)
; #pragma unroll
;             for (int b = 0; b < 2; ++b)
; #pragma unroll
;                 for (int m = 0; m < 4; ++m)
; #pragma unroll
;                     for (int n = 0; n < 2; ++n) acc[a][b][m][n] = (f32x4){0.f, 0.f, 0.f, 0.f};
;         cur = nxt; cA = nA; cB = nB; ++ui;
;     }
;     PG8_WAIT_V(0);
;     if (wr == 0) PG8_BAR;
;     PG8_BAR;
;     __device__ __forceinline__ void operator()(f32x4 (&acc)[2][2][4][2], const pg8::Unit& u, int wr, int wc, int fr, int fq) const {
;         const bool hi = fr >= 8;
;         const int row0 = u.pm * 256 + wr * 64 + (fr & 7), col = u.pn * 256 + wc * 64 + fq * 8 + (hi ? 32 : 0);
; #pragma unroll
;         for (int ai = 0; ai < 2; ++ai)
; #pragma unroll
;             for (int m = 0; m < 4; ++m) {
;                 const h8 x0 = pack8(acc[ai][0][m][0], acc[ai][0][m][1]), x1 = pack8(acc[ai][1][m][0], acc[ai][1][m][1]);
;                 const i32x4 snd = hi ? __builtin_bit_cast(i32x4, x0) : __builtin_bit_cast(i32x4, x1);
;                 i32x4 rcv;
; #pragma unroll
;                 for (int d = 0; d < 4; ++d) rcv[d] = __builtin_amdgcn_update_dpp(0, snd[d], 0x128  , 0xF, 0xF, false);
;                 const h8 rv = __builtin_bit_cast(h8, rcv);
;                 const h8 vA = hi ? rv : x0;
;                 const h8 vB = hi ? x1 : rv;
;                 half_t* rowp = O + (size_t)(row0 + ai * 128 + m * 16) * NIN + col;
;                 __builtin_nontemporal_store(vA, (h8*)rowp); __builtin_nontemporal_store(vB, (h8*)(rowp + (size_t)8 * NIN)); }
	v_cvt_pk_f16_f32 v45, v36, v37
	global_store_dwordx4 v[52:53], v[56:59], off nt
	v_cvt_pk_f16_f32 v50, v50, v51
	v_cvt_pk_f16_f32 v42, v42, v43
	v_cndmask_b32_e64 v41, v40, v48, s[4:5]
	v_cndmask_b32_e64 v36, v45, v44, s[4:5]
	v_mov_b32_e32 v49, v3
	v_mov_b32_e32 v52, v3
	v_cndmask_b32_e64 v43, v42, v50, s[4:5]
	v_cvt_pk_f16_f32 v46, v46, v47
	v_cvt_pk_f16_f32 v47, v38, v39
	v_mov_b32_dpp v49, v36 row_ror:8 row_mask:0xf bank_mask:0xf
	v_mov_b32_dpp v52, v41 row_ror:8 row_mask:0xf bank_mask:0xf
	v_mov_b32_e32 v41, v3
	v_cndmask_b32_e64 v38, v47, v46, s[4:5]
	v_mov_b32_e32 v51, v3
	v_mov_b32_dpp v41, v43 row_ror:8 row_mask:0xf bank_mask:0xf
	v_cndmask_b32_e64 v36, v44, v49, s[4:5]
	v_add_u32_e32 v44, 0x90, v146
	v_mov_b32_dpp v51, v38 row_ror:8 row_mask:0xf bank_mask:0xf
	v_cndmask_b32_e64 v43, v41, v42, s[4:5]
	v_cndmask_b32_e64 v42, v52, v40, s[4:5]
	v_cndmask_b32_e64 v40, v49, v45, s[4:5]
	v_mad_i64_i32 v[44:45], s[14:15], v44, s35, v[116:117]
	v_cndmask_b32_e64 v39, v50, v41, s[4:5]
	v_cndmask_b32_e64 v38, v48, v52, s[4:5]
	v_cndmask_b32_e64 v37, v46, v51, s[4:5]
	v_lshl_add_u64 v[44:45], v[44:45], 0, v[118:119]
	global_store_dwordx4 v[44:45], v[36:39], off nt
	v_cndmask_b32_e64 v41, v51, v47, s[4:5]
	v_cvt_pk_f16_f32 v32, v32, v33
	v_add_co_u32_e32 v36, vcc, s1, v44
	v_cvt_pk_f16_f32 v24, v24, v25
	s_nop 0
	v_addc_co_u32_e32 v37, vcc, 0, v45, vcc
	v_cvt_pk_f16_f32 v28, v28, v29
	v_cvt_pk_f16_f32 v29, v20, v21
	global_store_dwordx4 v[36:37], v[40:43], off nt
	v_cvt_pk_f16_f32 v34, v34, v35
	v_cvt_pk_f16_f32 v26, v26, v27
	v_cndmask_b32_e64 v25, v24, v32, s[4:5]
	v_cndmask_b32_e64 v20, v29, v28, s[4:5]
	v_mov_b32_e32 v33, v3
	v_mov_b32_e32 v36, v3
	v_cndmask_b32_e64 v27, v26, v34, s[4:5]
	v_cvt_pk_f16_f32 v30, v30, v31
	v_cvt_pk_f16_f32 v31, v22, v23
	v_mov_b32_dpp v33, v20 row_ror:8 row_mask:0xf bank_mask:0xf
	v_mov_b32_dpp v36, v25 row_ror:8 row_mask:0xf bank_mask:0xf
	v_mov_b32_e32 v25, v3
	v_cvt_pk_f16_f32 v16, v16, v17
	v_cvt_pk_f16_f32 v17, v4, v5
	v_cvt_pk_f16_f32 v5, v14, v15
	v_cvt_pk_f16_f32 v14, v10, v11
	v_cvt_pk_f16_f32 v10, v12, v13
	v_cvt_pk_f16_f32 v8, v8, v9
	v_cndmask_b32_e64 v22, v31, v30, s[4:5]
	v_mov_b32_e32 v35, v3
	v_mov_b32_dpp v25, v27 row_ror:8 row_mask:0xf bank_mask:0xf
	v_cndmask_b32_e64 v20, v28, v33, s[4:5]
	v_add_u32_e32 v28, 0xa0, v146
	v_cndmask_b32_e64 v9, v8, v10, s[4:5]
	v_mov_b32_e32 v12, v3
	v_mov_b32_dpp v35, v22 row_ror:8 row_mask:0xf bank_mask:0xf
	v_cndmask_b32_e64 v27, v25, v26, s[4:5]
	v_cndmask_b32_e64 v26, v36, v24, s[4:5]
	v_cndmask_b32_e64 v24, v33, v29, s[4:5]
	v_mad_i64_i32 v[28:29], s[14:15], v28, s35, v[116:117]
	v_cvt_pk_f16_f32 v18, v18, v19
	v_cvt_pk_f16_f32 v19, v6, v7
	v_cndmask_b32_e64 v4, v17, v16, s[4:5]
	v_mov_b32_dpp v12, v9 row_ror:8 row_mask:0xf bank_mask:0xf
	v_mov_b32_e32 v13, v3
	v_cndmask_b32_e64 v23, v34, v25, s[4:5]
	v_cndmask_b32_e64 v22, v32, v36, s[4:5]
	v_cndmask_b32_e64 v21, v30, v35, s[4:5]
	v_lshl_add_u64 v[28:29], v[28:29], 0, v[118:119]
	v_cndmask_b32_e64 v6, v19, v18, s[4:5]
	v_cndmask_b32_e64 v7, v14, v5, s[4:5]
	v_mov_b32_e32 v9, v3
	v_mov_b32_dpp v13, v4 row_ror:8 row_mask:0xf bank_mask:0xf
	v_mov_b32_e32 v11, v3
	v_cndmask_b32_e64 v4, v10, v12, s[4:5]
	v_cndmask_b32_e64 v8, v12, v8, s[4:5]
	v_add_u32_e32 v12, 0xb0, v146
	global_store_dwordx4 v[28:29], v[20:23], off nt
	v_mov_b32_dpp v9, v7 row_ror:8 row_mask:0xf bank_mask:0xf
	v_mov_b32_dpp v11, v6 row_ror:8 row_mask:0xf bank_mask:0xf
	v_add_co_u32_e32 v20, vcc, s1, v28
	v_cndmask_b32_e64 v6, v16, v13, s[4:5]
	v_cndmask_b32_e64 v10, v13, v17, s[4:5]
	v_mad_i64_i32 v[12:13], s[14:15], v12, s35, v[116:117]
	v_addc_co_u32_e32 v21, vcc, 0, v29, vcc
	v_cndmask_b32_e64 v7, v18, v11, s[4:5]
	v_cndmask_b32_e64 v5, v5, v9, s[4:5]
	v_lshl_add_u64 v[12:13], v[12:13], 0, v[118:119]
	global_store_dwordx4 v[12:13], v[4:7], off nt
	v_cndmask_b32_e64 v25, v35, v31, s[4:5]
	v_cndmask_b32_e64 v11, v11, v19, s[4:5]
	v_add_co_u32_e32 v4, vcc, 0x3c000, v12
	v_cndmask_b32_e64 v9, v9, v14, s[4:5]
	s_nop 0
	v_addc_co_u32_e32 v5, vcc, 0, v13, vcc
	s_and_b64 vcc, exec, s[6:7]
	s_mov_b32 s48, s0
	s_mov_b32 s49, s8
	s_mov_b64 s[18:19], s[12:13]
	s_mov_b64 s[14:15], s[10:11]
	global_store_dwordx4 v[20:21], v[24:27], off nt
	global_store_dwordx4 v[4:5], v[8:11], off nt
	s_cbranch_vccz .LBB0_329
	s_waitcnt vmcnt(0)
	v_readlane_b32 s42, v251, 7
	v_readlane_b32 s46, v251, 9
	v_readlane_b32 s48, v251, 13
	s_cmpk_gt_u32 s20, 0xff
	v_readlane_b32 s43, v251, 8
	v_readlane_b32 s47, v251, 10
	v_readlane_b32 s49, v251, 14
	s_cbranch_scc1 .LBB0_336
	s_barrier

; __global__ void __launch_bounds__(512, 2) hybrid_fwd(Params p) {
	.amdhsa_kernel _Z10hybrid_fwd6Params
		.amdhsa_group_segment_fixed_size 0
		.amdhsa_private_segment_fixed_size 0
		.amdhsa_kernarg_size 368
		.amdhsa_user_sgpr_count 2
		.amdhsa_user_sgpr_dispatch_ptr 0
		.amdhsa_user_sgpr_queue_ptr 0
		.amdhsa_user_sgpr_kernarg_segment_ptr 1
		.amdhsa_user_sgpr_dispatch_id 0
		.amdhsa_user_sgpr_kernarg_preload_length 0
		.amdhsa_user_sgpr_kernarg_preload_offset 0
		.amdhsa_user_sgpr_private_segment_size 0
		.amdhsa_uses_dynamic_stack 0
		.amdhsa_enable_private_segment 0
		.amdhsa_system_sgpr_workgroup_id_x 1
		.amdhsa_system_sgpr_workgroup_id_y 0
		.amdhsa_system_sgpr_workgroup_id_z 0
		.amdhsa_system_sgpr_workgroup_info 0
		.amdhsa_system_vgpr_workitem_id 2
		.amdhsa_next_free_vgpr 254
		.amdhsa_next_free_sgpr 102
		.amdhsa_accum_offset 256
		.amdhsa_reserve_vcc 1
		.amdhsa_float_round_mode_32 0
		.amdhsa_float_round_mode_16_64 0
		.amdhsa_float_denorm_mode_32 3
		.amdhsa_float_denorm_mode_16_64 3
		.amdhsa_dx10_clamp 1
		.amdhsa_ieee_mode 1
		.amdhsa_fp16_overflow 0
		.amdhsa_tg_split 0
		.amdhsa_exception_fp_ieee_invalid_op 0
		.amdhsa_exception_fp_denorm_src 0
		.amdhsa_exception_fp_ieee_div_zero 0
		.amdhsa_exception_fp_ieee_overflow 0
		.amdhsa_exception_fp_ieee_underflow 0
		.amdhsa_exception_fp_ieee_inexact 0
		.amdhsa_exception_int_div_zero 0
	.end_amdhsa_kernel

; __global__ void __launch_bounds__(512, 2) hybrid_fwd(Params p) {
.Lfunc_end0:
	.size	_Z10hybrid_fwd6Params, .Lfunc_end0-_Z10hybrid_fwd6Params
	.set _Z10hybrid_fwd6Params.num_vgpr, 254
	.set _Z10hybrid_fwd6Params.num_agpr, 0
	.set _Z10hybrid_fwd6Params.numbered_sgpr, 102
	.set _Z10hybrid_fwd6Params.num_named_barrier, 0
	.set _Z10hybrid_fwd6Params.private_seg_size, 0
	.set _Z10hybrid_fwd6Params.uses_vcc, 1
	.set _Z10hybrid_fwd6Params.uses_flat_scratch, 0
	.set _Z10hybrid_fwd6Params.has_dyn_sized_stack, 0
	.set _Z10hybrid_fwd6Params.has_recursion, 0
	.set _Z10hybrid_fwd6Params.has_indirect_call, 0

; __global__ void __launch_bounds__(512, 2) hybrid_fwd(Params p) {
amdhsa.kernels:
  - .agpr_count:     0
    .args:
      - .offset:         0
        .size:           112
        .value_kind:     by_value
      - .offset:         112
        .size:           4
        .value_kind:     hidden_block_count_x
      - .offset:         116
        .size:           4
        .value_kind:     hidden_block_count_y
      - .offset:         120
        .size:           4
        .value_kind:     hidden_block_count_z
      - .offset:         124
        .size:           2
        .value_kind:     hidden_group_size_x
      - .offset:         126
        .size:           2
        .value_kind:     hidden_group_size_y
      - .offset:         128
        .size:           2
        .value_kind:     hidden_group_size_z
      - .offset:         130
        .size:           2
        .value_kind:     hidden_remainder_x
      - .offset:         132
        .size:           2
        .value_kind:     hidden_remainder_y
      - .offset:         134
        .size:           2
        .value_kind:     hidden_remainder_z
      - .offset:         152
        .size:           8
        .value_kind:     hidden_global_offset_x
      - .offset:         160
        .size:           8
        .value_kind:     hidden_global_offset_y
      - .offset:         168
        .size:           8
        .value_kind:     hidden_global_offset_z
      - .offset:         176
        .size:           2
        .value_kind:     hidden_grid_dims
      - .offset:         200
        .size:           8
        .value_kind:     hidden_multigrid_sync_arg
      - .offset:         232
        .size:           4
        .value_kind:     hidden_dynamic_lds_size
    .group_segment_fixed_size: 0
    .kernarg_segment_align: 8
    .kernarg_segment_size: 368
    .language:       OpenCL C
    .language_version:
      - 2
      - 0
    .max_flat_workgroup_size: 512
    .name:           _Z10hybrid_fwd6Params
    .private_segment_fixed_size: 0
    .sgpr_count:     108
    .sgpr_spill_count: 197
    .symbol:         _Z10hybrid_fwd6Params.kd
    .uniform_work_group_size: 1
    .uses_dynamic_stack: false
    .vgpr_count:     254
    .vgpr_spill_count: 0
    .wavefront_size: 64
